# MoE expert-weight fp8 conversion moved out of prologue and LN phase into attention phase entry on 64 designated workgroups (overlaps with attention on the other workgroups)
# speedup vs baseline: 1.0271x; 1.0271x over previous
; #define LAS __attribute__((address_space(3)))
; __device__ __forceinline__ int oi(int k) { asm volatile("" : "+s"(k)); return k; }
; #define opq(p) ((p) + oz())
; __device__ __forceinline__ const float* gfp(const float* p) { ASSUME_GLOBAL(p); return p; }
; #define ws opq(a.ws)
; __device__ __forceinline__ void cvt_moe(const Args& a, int ml, LAS float* scr, int gw, int NGW, int lane) {
;     asm volatile("" : "+v"(lane));
;     constexpr int I_GU = (DM / 64) * (2 * FFE / 32), I_D = (FFE / 64) * (DM / 32), I_E = I_GU + I_D;
;     const float* wg = gfp(a.in[oi(19)]) + (size_t)ml * NEXP * DM * FFE; const float* wu = gfp(a.in[oi(20)]) + (size_t)ml * NEXP * DM * FFE; const float* wd = gfp(a.in[oi(21)]) + (size_t)ml * NEXP * FFE * DM;
;     unsigned char* wsl = opq(a.ws); bf16_t* mgu = (bf16_t*)(wsl + WS_MGU); bf16_t* md = (bf16_t*)(wsl + WS_MD);
;     for (int it = gw; it < NEXP * I_E; it += NGW) {
;         const int e = it / I_E; int r = it % I_E;
;         if (r < I_GU) { MapGU f{wg + (size_t)e * DM * FFE, wu + (size_t)e * DM * FFE, FFE}; cvt_item<MapGU, true>(f, nullptr, DM, (bf16_t*)((unsigned char*)mgu + (size_t)e * 2 * FFE * DM), scr, r, 2 * FFE / 32, lane, W8_GU); }
;         else { r -= I_GU; MapPlain f{wd + (size_t)e * FFE * DM, DM}; cvt_item<MapPlain, true>(f, nullptr, FFE, (bf16_t*)((unsigned char*)md + (size_t)e * DM * FFE), scr, r, DM / 32, lane, W8_D); }
;     }
; }
.LBB0_90:
	v_mov_b32_e32 v1, v166
	v_readlane_b32 s72, v251, 6
	s_mov_b32 s26, s86
	s_cmp_gt_i32 s86, 0xa7ff
	s_mov_b32 s10, 19
	v_and_b32_e32 v2, 63, v1
	s_mov_b32 s8, 20
	s_mov_b32 s4, 21
	s_mov_b64 s[12:13], 0
	v_readlane_b32 s73, v251, 7
	s_branch .LBB0_103
	s_ashr_i32 s11, s10, 31
	s_lshl_b64 s[10:11], s[10:11], 3
	s_add_u32 s16, s72, s10
	s_addc_u32 s17, s73, s11
	s_ashr_i32 s9, s8, 31
	s_lshl_b64 s[8:9], s[8:9], 3
	s_add_u32 s18, s72, s8
	s_addc_u32 s19, s73, s9
	s_ashr_i32 s5, s4, 31
	s_lshl_b64 s[4:5], s[4:5], 3
	s_add_u32 s20, s72, s4
	s_addc_u32 s21, s73, s5
	s_waitcnt lgkmcnt(0)
	s_add_u32 s12, s6, s12
	s_addc_u32 s14, s7, s13
	s_add_u32 s13, s12, 0x4400000
	s_load_dwordx2 s[4:5], s[16:17], 0x0
	s_load_dwordx2 s[8:9], s[18:19], 0x0
	s_load_dwordx2 s[10:11], s[20:21], 0x0
	s_addc_u32 s24, s14, 0
	s_mov_b32 s16, s26
	s_add_u32 s26, s12, 0xb400000
	v_lshlrev_b32_e32 v3, 2, v2
	s_addc_u32 s27, s14, 0
	v_ashrrev_i32_e32 v1, 3, v2
	v_and_b32_e32 v26, 28, v3
	v_readlane_b32 s14, v251, 5
	s_movk_i32 s12, 0x84
	v_lshlrev_b32_e32 v2, 3, v2
	v_lshl_add_u32 v10, v26, 2, s14
	v_mul_lo_u32 v11, v1, s12
	v_and_b32_e32 v4, 56, v2
	s_lshl_b32 s12, s16, 5
	v_mov_b32_e32 v3, 0
	v_mul_u32_u24_e32 v2, 0x84, v4
	v_lshlrev_b32_e32 v9, 2, v1
	s_add_i32 s28, s12, 0xfffe4000
	s_lshl_b32 s12, s16, 1
	v_add_u32_e32 v10, v10, v11
	v_add_u32_e32 v6, 8, v1
	v_add_u32_e32 v7, 16, v1
	v_add_u32_e32 v8, 24, v1
	v_mov_b32_e32 v5, v3
	v_add3_u32 v9, s14, v2, v9
	s_lshl_b32 s29, s94, 8
	s_add_i32 s30, s12, 0xffffe400
	s_lshl_b32 s31, s94, 4
	s_mov_b32 s34, 0x8000
	s_mov_b32 s35, 0x10000
	s_mov_b32 s36, 0x18000
	s_mov_b32 s37, 0x20000
	s_mov_b32 s38, 0x28000
	s_mov_b32 s39, 0x30000
	s_mov_b32 s40, 0x38000
	s_mov_b32 s12, 0x43000000
	v_add_u32_e32 v11, 0x420, v10
	v_add_u32_e32 v12, 0x428, v10
	v_add_u32_e32 v13, 0x840, v10
	v_add_u32_e32 v14, 0x848, v10
	v_add_u32_e32 v15, 0xc60, v10
	v_add_u32_e32 v16, 0xc68, v10
	v_add_u32_e32 v17, 0x1080, v10
	v_add_u32_e32 v18, 0x1088, v10
	v_add_u32_e32 v19, 0x14a0, v10
	v_add_u32_e32 v20, 0x14a8, v10
	v_add_u32_e32 v21, 0x18c0, v10
	v_add_u32_e32 v22, 0x18c8, v10
	v_add_u32_e32 v23, 0x1ce0, v10
	v_add_u32_e32 v24, 0x1ce8, v10
	s_movk_i32 s41, 0xe00
	s_movk_i32 s42, 0x3800
	s_mov_b32 s14, 0x42800000
	v_lshlrev_b32_e32 v2, 2, v26
	s_mov_b32 s43, s16
	s_branch .LBB0_94

; #define LAS __attribute__((address_space(3)))
; __device__ __forceinline__ int oi(int k) { asm volatile("" : "+s"(k)); return k; }
; #define opq(p) ((p) + oz())
; __device__ __forceinline__ const float* gfp(const float* p) { ASSUME_GLOBAL(p); return p; }
;     __device__ __forceinline__ bool contig(int n0) const { return (n0 % 192) < 128; }
; #define ws opq(a.ws)
;     const int kb = item / nblk, nb = item % nblk, k0 = 64 * kb, n0 = 32 * nb;
;     if (f.contig(n0)) {
;         const float* base; int ld; float sc; f(n0, base, ld, sc); sc *= mul;
;         const int r8 = lane >> 3, c4 = (lane & 7) * 4;
;         f32x4 v[8];
; #pragma unroll
;         for (int i = 0; i < 8; ++i) v[i] = __builtin_nontemporal_load((const f32x4*)(base + (size_t)(k0 + 8 * i + r8) * ld + c4));
; #pragma unroll
;         for (int i = 0; i < 8; ++i) { const int kk = 8 * i + r8; const float m = kscale ? sc * kscale[k0 + kk] : sc;
;             scr[kk * 33 + c4 + 0] = v[i][0] * m; scr[kk * 33 + c4 + 1] = v[i][1] * m; scr[kk * 33 + c4 + 2] = v[i][2] * m; scr[kk * 33 + c4 + 3] = v[i][3] * m; }
; __device__ __forceinline__ void cvt_moe(const Args& a, int ml, LAS float* scr, int gw, int NGW, int lane) {
;     asm volatile("" : "+v"(lane));
;     constexpr int I_GU = (DM / 64) * (2 * FFE / 32), I_D = (FFE / 64) * (DM / 32), I_E = I_GU + I_D;
;     const float* wg = gfp(a.in[oi(19)]) + (size_t)ml * NEXP * DM * FFE; const float* wu = gfp(a.in[oi(20)]) + (size_t)ml * NEXP * DM * FFE; const float* wd = gfp(a.in[oi(21)]) + (size_t)ml * NEXP * FFE * DM;
;     unsigned char* wsl = opq(a.ws); bf16_t* mgu = (bf16_t*)(wsl + WS_MGU); bf16_t* md = (bf16_t*)(wsl + WS_MD);
;     for (int it = gw; it < NEXP * I_E; it += NGW) {
;         const int e = it / I_E; int r = it % I_E;
;         if (r < I_GU) { MapGU f{wg + (size_t)e * DM * FFE, wu + (size_t)e * DM * FFE, FFE}; cvt_item<MapGU, true>(f, nullptr, DM, (bf16_t*)((unsigned char*)mgu + (size_t)e * 2 * FFE * DM), scr, r, 2 * FFE / 32, lane, W8_GU); }
;         else { r -= I_GU; MapPlain f{wd + (size_t)e * FFE * DM, DM}; cvt_item<MapPlain, true>(f, nullptr, FFE, (bf16_t*)((unsigned char*)md + (size_t)e * DM * FFE), scr, r, DM / 32, lane, W8_D); }
;     }
; }
.LBB0_513:
	s_andn2_b64 vcc, exec, s[0:1]
	s_cbranch_vccnz .LBB0_930
	s_mov_b32 s91, s27
	v_writelane_b32 v254, s24, 41
	s_lshl_b64 s[0:1], s[90:91], 10
	v_writelane_b32 v254, s0, 43
	s_lshl_b32 s26, s90, 8
	s_mov_b64 s[2:3], 0
	v_writelane_b32 v254, s1, 44
	s_lshl_b32 s0, s90, 7
	s_add_u32 s4, s14, s2
	s_addc_u32 s5, s15, s3
	s_lshl_b64 s[2:3], s[90:91], 2
	s_add_u32 s2, s4, s2
	s_addc_u32 s3, s5, s3
	v_writelane_b32 v254, s2, 45
	s_mov_b32 s1, s27
	s_lshl_b64 s[0:1], s[0:1], 2
	v_writelane_b32 v254, s3, 46
	s_lshl_b64 s[2:3], s[26:27], 2
	v_writelane_b32 v254, s2, 47
	s_nop 1
	v_writelane_b32 v254, s3, 48
	v_writelane_b32 v254, s0, 49
	s_nop 1
	v_writelane_b32 v254, s1, 50
	s_mov_b32 s0, s90
	v_readlane_b32 s41, v254, 17
	v_writelane_b32 v254, s0, 51
	s_nop 1
	v_writelane_b32 v254, s1, 52
	s_cmp_eq_u32 s90, 0
	s_cbranch_scc1 .Lcve_go
	s_cmp_eq_u32 s90, 2
	s_cbranch_scc0 .Lcve_done
.Lcve_go:
	v_readlane_b32 s101, v251, 2
	s_nop 3
	s_and_b32 s100, s101, 3
	s_cmp_eq_u32 s100, 0
	s_cbranch_scc0 .Lcve_done
	v_writelane_b32 v145, s8, 0
	v_writelane_b32 v145, s9, 1
	v_writelane_b32 v145, s10, 2
	v_writelane_b32 v145, s11, 3
	v_writelane_b32 v145, s12, 4
	v_writelane_b32 v145, s13, 5
	v_writelane_b32 v145, s14, 6
	v_writelane_b32 v145, s15, 7
	v_writelane_b32 v145, s16, 8
	v_writelane_b32 v145, s17, 9
	v_writelane_b32 v145, s18, 10
	v_writelane_b32 v145, s19, 11
	v_writelane_b32 v145, s20, 12
	v_writelane_b32 v145, s21, 13
	v_writelane_b32 v145, s22, 14
	v_writelane_b32 v145, s23, 15
	v_writelane_b32 v145, s24, 16
	v_writelane_b32 v145, s25, 17
	v_writelane_b32 v145, s26, 18
	v_writelane_b32 v145, s27, 19
	v_writelane_b32 v145, s28, 20
	v_writelane_b32 v145, s29, 21
	v_writelane_b32 v145, s30, 22
	v_writelane_b32 v145, s31, 23
	v_writelane_b32 v145, s32, 24
	v_writelane_b32 v145, s33, 25
	v_writelane_b32 v145, s34, 26
	v_writelane_b32 v145, s35, 27
	v_writelane_b32 v145, s36, 28
	v_writelane_b32 v145, s37, 29
	v_writelane_b32 v145, s38, 30
	v_writelane_b32 v145, s39, 31
	v_writelane_b32 v145, s40, 32
	v_writelane_b32 v145, s41, 33
	v_writelane_b32 v145, s42, 34
	v_writelane_b32 v145, s43, 35
	v_writelane_b32 v145, s44, 36
	v_writelane_b32 v145, s45, 37
	v_writelane_b32 v145, s46, 38
	v_writelane_b32 v145, s47, 39
	s_mov_b64 s[8:9], exec
	s_mov_b64 exec, -1
	v_readlane_b32 s10, v251, 6
	v_readlane_b32 s11, v251, 7
	s_nop 3
	s_load_dwordx2 s[12:13], s[10:11], 0x98
	s_load_dwordx2 s[14:15], s[10:11], 0xa0
	s_load_dwordx2 s[16:17], s[10:11], 0xa8
	s_load_dwordx2 s[18:19], s[10:11], 0xb8
	v_and_b32_e32 v5, 63, v166
	v_lshrrev_b32_e32 v6, 3, v5
	v_and_b32_e32 v7, 7, v5
	v_lshlrev_b32_e32 v10, 3, v7
	v_readfirstlane_b32 s46, v166
	v_mul_u32_u24_e32 v8, 0x84, v6
	v_mul_u32_u24_e32 v9, 0x420, v7
	v_lshlrev_b32_e32 v7, 4, v7
	s_lshr_b32 s46, s46, 6
	s_lshl_b32 s47, s46, 14
	v_add3_u32 v8, v8, v7, s47
	v_lshl_add_u32 v9, v6, 2, v9
	v_add_u32_e32 v9, s47, v9
	v_add_u32_e32 v128, 0, v8
	v_add_u32_e32 v129, 1056, v8
	v_add_u32_e32 v130, 2112, v8
	v_add_u32_e32 v131, 3168, v8
	v_add_u32_e32 v132, 4224, v8
	v_add_u32_e32 v133, 5280, v8
	v_add_u32_e32 v134, 6336, v8
	v_add_u32_e32 v135, 7392, v8
	s_movk_i32 s41, 0x3800
	v_mad_u32_u24 v11, v6, s41, v7
	v_add_u32_e32 v12, 0x1c000, v11
	v_add_u32_e32 v13, 0x1c000, v12
	v_add_u32_e32 v14, 0x1c000, v13
	v_add_u32_e32 v15, 0x1c000, v14
	v_add_u32_e32 v16, 0x1c000, v15
	v_add_u32_e32 v17, 0x1c000, v16
	v_add_u32_e32 v18, 0x1c000, v17
	s_movk_i32 s41, 0x1000
	v_mad_u32_u24 v136, v6, s41, v7
	v_add_u32_e32 v137, 0x8000, v136
	v_add_u32_e32 v138, 0x8000, v137
	v_add_u32_e32 v139, 0x8000, v138
	v_add_u32_e32 v140, 0x8000, v139
	v_add_u32_e32 v141, 0x8000, v140
	v_add_u32_e32 v142, 0x8000, v141
	v_add_u32_e32 v143, 0x8000, v142
	v_lshl_add_u32 v19, v6, 10, v10
	v_add_u32_e32 v20, 0x2000, v19
	v_add_u32_e32 v21, 0x2000, v20
	v_add_u32_e32 v22, 0x2000, v21
	s_movk_i32 s41, 0xe00
	v_mad_u32_u24 v144, v6, s41, v10
	v_add_u32_e32 v23, 0x7000, v144
	v_add_u32_e32 v5, 0x7000, v23
	v_add_u32_e32 v7, 0x7000, v5
	s_lshr_b32 s42, s101, 2
	s_lshl_b32 s42, s42, 3
	s_add_u32 s20, s42, s46
	s_movk_i32 s21, 84
	s_mov_b32 s22, s20
	s_lshr_b32 s41, s90, 1
	s_mul_i32 s41, s41, 0x7000000
	s_waitcnt lgkmcnt(0)
	s_add_u32 s12, s12, s41
	s_addc_u32 s13, s13, 0
	s_add_u32 s14, s14, s41
	s_addc_u32 s15, s15, 0
	s_add_u32 s16, s16, s41
	s_addc_u32 s17, s17, 0
.Lcve_loop:
	s_cmp_lt_u32 s21, 2
	s_cbranch_scc1 .Lcve_tail
	s_lshr_b32 s23, s22, 8
	s_mul_i32 s23, s23, 3121
	s_lshr_b32 s23, s23, 16
	s_mul_i32 s24, s23, 5376
	s_sub_u32 s24, s22, s24
	s_cmp_lt_u32 s24, 3584
	s_cbranch_scc0 .Lcve_DA1
	s_lshr_b32 s25, s24, 5
	s_mul_i32 s25, s25, 9363
	s_lshr_b32 s25, s25, 16
	s_mul_i32 s41, s25, 224
	s_sub_u32 s41, s24, s41
	s_and_b32 s42, s41, 7
	s_cmp_lt_u32 s42, 4
	s_cselect_b32 s26, s12, s14
	s_cselect_b32 s27, s13, s15
	s_mul_i32 s43, s23, 14680064
	s_mul_i32 s44, s25, 917504
	s_add_u32 s43, s43, s44
	s_lshr_b32 s44, s41, 3
	s_lshl_b32 s44, s44, 9
	s_add_u32 s43, s43, s44
	s_and_b32 s44, s42, 3
	s_lshl_b32 s44, s44, 7
	s_add_u32 s43, s43, s44
	s_add_u32 s26, s26, s43
	s_addc_u32 s27, s27, 0
	s_mul_i32 s43, s23, 7340032
	s_lshl_b32 s44, s41, 15
	s_add_u32 s43, s43, s44
	s_lshl_b32 s44, s25, 6
	s_add_u32 s43, s43, s44
	s_add_u32 s43, s43, 0x4400000
	s_add_u32 s28, s18, s43
	s_addc_u32 s29, s19, 0
	s_mov_b32 s30, 0
	s_mov_b32 s32, 0x42800000
	s_branch .Lcve_EA1
.Lcve_DA1:
	s_sub_u32 s24, s24, 3584
	s_lshr_b32 s25, s24, 5
	s_and_b32 s41, s24, 31
	s_mul_i32 s43, s23, 14680064
	s_lshl_b32 s44, s25, 18
	s_add_u32 s43, s43, s44
	s_lshl_b32 s44, s41, 7
	s_add_u32 s43, s43, s44
	s_add_u32 s26, s16, s43
	s_addc_u32 s27, s17, 0
	s_mul_i32 s43, s23, 3670016
	s_mul_i32 s44, s41, 114688
	s_add_u32 s43, s43, s44
	s_lshl_b32 s44, s25, 6
	s_add_u32 s43, s43, s44
	s_add_u32 s43, s43, 0xb400000
	s_add_u32 s28, s18, s43
	s_addc_u32 s29, s19, 0
	s_mov_b32 s30, 1
	s_mov_b32 s32, 0x43000000
; #define LAS __attribute__((address_space(3)))
; __device__ __forceinline__ unsigned cvt_pk_bf16(float lo, float hi) { unsigned r; asm volatile("v_cvt_pk_bf16_f32 %0, %1, %2" : "=v"(r) : "v"(lo), "v"(hi)); return r; }
; __device__ __forceinline__ unsigned cvt4_fp8(float a, float b, float c, float d) { unsigned w = __builtin_amdgcn_cvt_pk_fp8_f32(a, b, 0u, false); return (unsigned)__builtin_amdgcn_cvt_pk_fp8_f32(c, d, (int)w, true); }
; #define LDS_WAIT() asm volatile("s_waitcnt lgkmcnt(0)" ::: "memory")
;     const int kb = item / nblk, nb = item % nblk, k0 = 64 * kb, n0 = 32 * nb;
;     if (f.contig(n0)) {
;         const float* base; int ld; float sc; f(n0, base, ld, sc); sc *= mul;
;         const int r8 = lane >> 3, c4 = (lane & 7) * 4;
;         f32x4 v[8];
; #pragma unroll
;         for (int i = 0; i < 8; ++i) v[i] = __builtin_nontemporal_load((const f32x4*)(base + (size_t)(k0 + 8 * i + r8) * ld + c4));
; #pragma unroll
;         for (int i = 0; i < 8; ++i) { const int kk = 8 * i + r8; const float m = kscale ? sc * kscale[k0 + kk] : sc;
;             scr[kk * 33 + c4 + 0] = v[i][0] * m; scr[kk * 33 + c4 + 1] = v[i][1] * m; scr[kk * 33 + c4 + 2] = v[i][2] * m; scr[kk * 33 + c4 + 3] = v[i][3] * m; }
;     } else {
;         const float* src; int ld; float sc; f(n0 + (lane & 31), src, ld, sc); sc *= mul;
; #pragma unroll 8
;         for (int i = 0; i < 32; ++i) { const int kk = 2 * i + (lane >> 5); float v = src[(size_t)(k0 + kk) * ld] * sc; if (kscale) v *= kscale[k0 + kk]; scr[kk * 33 + (lane & 31)] = v; }
;     }
;     LDS_WAIT(); asm volatile("" ::: "memory");
;     const int c = lane & 7;
; #pragma unroll
;     for (int j = 0; j < 4; ++j) { const int n = (lane >> 3) + 8 * j; const LAS float* s = scr + (8 * c) * 33 + n;
;         if constexpr (F8OUT) {
;             u32x2 o; o.x = cvt4_fp8(s[0 * 33], s[1 * 33], s[2 * 33], s[3 * 33]); o.y = cvt4_fp8(s[4 * 33], s[5 * 33], s[6 * 33], s[7 * 33]);
;             *(u32x2*)((unsigned char*)WT + (size_t)(n0 + n) * K + k0 + 8 * c) = o;
;         } else {
;             u32x4 o; o.x = cvt_pk_bf16(s[0 * 33], s[1 * 33]); o.y = cvt_pk_bf16(s[2 * 33], s[3 * 33]); o.z = cvt_pk_bf16(s[4 * 33], s[5 * 33]); o.w = cvt_pk_bf16(s[6 * 33], s[7 * 33]);
;             *(u32x4*)(WT + (size_t)(n0 + n) * K + k0 + 8 * c) = o; } }
;     LDS_WAIT(); asm volatile("" ::: "memory");
; }
.Lcve_EA1:
	s_add_u32 s22, s22, 512
	s_lshr_b32 s23, s22, 8
	s_mul_i32 s23, s23, 3121
	s_lshr_b32 s23, s23, 16
	s_mul_i32 s24, s23, 5376
	s_sub_u32 s24, s22, s24
	s_cmp_lt_u32 s24, 3584
	s_cbranch_scc0 .Lcve_DB2
	s_lshr_b32 s25, s24, 5
	s_mul_i32 s25, s25, 9363
	s_lshr_b32 s25, s25, 16
	s_mul_i32 s41, s25, 224
	s_sub_u32 s41, s24, s41
	s_and_b32 s42, s41, 7
	s_cmp_lt_u32 s42, 4
	s_cselect_b32 s34, s12, s14
	s_cselect_b32 s35, s13, s15
	s_mul_i32 s43, s23, 14680064
	s_mul_i32 s44, s25, 917504
	s_add_u32 s43, s43, s44
	s_lshr_b32 s44, s41, 3
	s_lshl_b32 s44, s44, 9
	s_add_u32 s43, s43, s44
	s_and_b32 s44, s42, 3
	s_lshl_b32 s44, s44, 7
	s_add_u32 s43, s43, s44
	s_add_u32 s34, s34, s43
	s_addc_u32 s35, s35, 0
	s_mul_i32 s43, s23, 7340032
	s_lshl_b32 s44, s41, 15
	s_add_u32 s43, s43, s44
	s_lshl_b32 s44, s25, 6
	s_add_u32 s43, s43, s44
	s_add_u32 s43, s43, 0x4400000
	s_add_u32 s36, s18, s43
	s_addc_u32 s37, s19, 0
	s_mov_b32 s38, 0
	s_mov_b32 s40, 0x42800000
	s_branch .Lcve_EB2
.Lcve_DB2:
	s_sub_u32 s24, s24, 3584
	s_lshr_b32 s25, s24, 5
	s_and_b32 s41, s24, 31
	s_mul_i32 s43, s23, 14680064
	s_lshl_b32 s44, s25, 18
	s_add_u32 s43, s43, s44
	s_lshl_b32 s44, s41, 7
	s_add_u32 s43, s43, s44
	s_add_u32 s34, s16, s43
	s_addc_u32 s35, s17, 0
	s_mul_i32 s43, s23, 3670016
	s_mul_i32 s44, s41, 114688
	s_add_u32 s43, s43, s44
	s_lshl_b32 s44, s25, 6
	s_add_u32 s43, s43, s44
	s_add_u32 s43, s43, 0xb400000
	s_add_u32 s36, s18, s43
	s_addc_u32 s37, s19, 0
	s_mov_b32 s38, 1
	s_mov_b32 s40, 0x43000000
.Lcve_EB2:
	s_add_u32 s22, s22, 512
	s_cmp_eq_u32 s30, 0
	s_cbranch_scc0 .Lcve_iA3d
	global_load_dwordx4 v[24:27], v11, s[26:27] nt
	global_load_dwordx4 v[28:31], v12, s[26:27] nt
	global_load_dwordx4 v[32:35], v13, s[26:27] nt
	global_load_dwordx4 v[36:39], v14, s[26:27] nt
	global_load_dwordx4 v[40:43], v15, s[26:27] nt
	global_load_dwordx4 v[44:47], v16, s[26:27] nt
	global_load_dwordx4 v[48:51], v17, s[26:27] nt
	global_load_dwordx4 v[52:55], v18, s[26:27] nt
	s_branch .Lcve_iA3e
.Lcve_iA3d:
	global_load_dwordx4 v[24:27], v136, s[26:27] nt
	global_load_dwordx4 v[28:31], v137, s[26:27] nt
	global_load_dwordx4 v[32:35], v138, s[26:27] nt
	global_load_dwordx4 v[36:39], v139, s[26:27] nt
	global_load_dwordx4 v[40:43], v140, s[26:27] nt
	global_load_dwordx4 v[44:47], v141, s[26:27] nt
	global_load_dwordx4 v[48:51], v142, s[26:27] nt
	global_load_dwordx4 v[52:55], v143, s[26:27] nt
.Lcve_iA3e:
	s_cmp_eq_u32 s38, 0
	s_cbranch_scc0 .Lcve_iB4d
	global_load_dwordx4 v[56:59], v11, s[34:35] nt
	global_load_dwordx4 v[60:63], v12, s[34:35] nt
	global_load_dwordx4 v[64:67], v13, s[34:35] nt
	global_load_dwordx4 v[68:71], v14, s[34:35] nt
	global_load_dwordx4 v[72:75], v15, s[34:35] nt
	global_load_dwordx4 v[76:79], v16, s[34:35] nt
	global_load_dwordx4 v[80:83], v17, s[34:35] nt
	global_load_dwordx4 v[84:87], v18, s[34:35] nt
	s_branch .Lcve_iB4e
.Lcve_iB4d:
	global_load_dwordx4 v[56:59], v136, s[34:35] nt
	global_load_dwordx4 v[60:63], v137, s[34:35] nt
	global_load_dwordx4 v[64:67], v138, s[34:35] nt
	global_load_dwordx4 v[68:71], v139, s[34:35] nt
	global_load_dwordx4 v[72:75], v140, s[34:35] nt
	global_load_dwordx4 v[76:79], v141, s[34:35] nt
	global_load_dwordx4 v[80:83], v142, s[34:35] nt
	global_load_dwordx4 v[84:87], v143, s[34:35] nt
.Lcve_iB4e:
	s_waitcnt vmcnt(8)
	v_pk_mul_f32 v[24:25], v[24:25], s[32:33] op_sel_hi:[1,0]
	v_pk_mul_f32 v[26:27], v[26:27], s[32:33] op_sel_hi:[1,0]
	ds_write2_b32 v128, v24, v25 offset1:1
	ds_write2_b32 v128, v26, v27 offset0:2 offset1:3
	v_pk_mul_f32 v[28:29], v[28:29], s[32:33] op_sel_hi:[1,0]
	v_pk_mul_f32 v[30:31], v[30:31], s[32:33] op_sel_hi:[1,0]
	ds_write2_b32 v129, v28, v29 offset1:1
	ds_write2_b32 v129, v30, v31 offset0:2 offset1:3
	v_pk_mul_f32 v[32:33], v[32:33], s[32:33] op_sel_hi:[1,0]
	v_pk_mul_f32 v[34:35], v[34:35], s[32:33] op_sel_hi:[1,0]
	ds_write2_b32 v130, v32, v33 offset1:1
	ds_write2_b32 v130, v34, v35 offset0:2 offset1:3
	v_pk_mul_f32 v[36:37], v[36:37], s[32:33] op_sel_hi:[1,0]
	v_pk_mul_f32 v[38:39], v[38:39], s[32:33] op_sel_hi:[1,0]
	ds_write2_b32 v131, v36, v37 offset1:1
	ds_write2_b32 v131, v38, v39 offset0:2 offset1:3
	v_pk_mul_f32 v[40:41], v[40:41], s[32:33] op_sel_hi:[1,0]
	v_pk_mul_f32 v[42:43], v[42:43], s[32:33] op_sel_hi:[1,0]
	ds_write2_b32 v132, v40, v41 offset1:1
	ds_write2_b32 v132, v42, v43 offset0:2 offset1:3
	v_pk_mul_f32 v[44:45], v[44:45], s[32:33] op_sel_hi:[1,0]
	v_pk_mul_f32 v[46:47], v[46:47], s[32:33] op_sel_hi:[1,0]
	ds_write2_b32 v133, v44, v45 offset1:1
	ds_write2_b32 v133, v46, v47 offset0:2 offset1:3
	v_pk_mul_f32 v[48:49], v[48:49], s[32:33] op_sel_hi:[1,0]
	v_pk_mul_f32 v[50:51], v[50:51], s[32:33] op_sel_hi:[1,0]
	ds_write2_b32 v134, v48, v49 offset1:1
	ds_write2_b32 v134, v50, v51 offset0:2 offset1:3
	v_pk_mul_f32 v[52:53], v[52:53], s[32:33] op_sel_hi:[1,0]
	v_pk_mul_f32 v[54:55], v[54:55], s[32:33] op_sel_hi:[1,0]
	ds_write2_b32 v135, v52, v53 offset1:1
	ds_write2_b32 v135, v54, v55 offset0:2 offset1:3
	s_waitcnt lgkmcnt(0)
	ds_read2_b32 v[88:89], v9 offset0:0 offset1:33
	ds_read2_b32 v[90:91], v9 offset0:66 offset1:99
	ds_read2_b32 v[92:93], v9 offset0:132 offset1:165
	ds_read2_b32 v[94:95], v9 offset0:198 offset1:231
	ds_read2_b32 v[96:97], v9 offset0:8 offset1:41
	ds_read2_b32 v[98:99], v9 offset0:74 offset1:107
	ds_read2_b32 v[100:101], v9 offset0:140 offset1:173
	ds_read2_b32 v[102:103], v9 offset0:206 offset1:239
	ds_read2_b32 v[104:105], v9 offset0:16 offset1:49
	ds_read2_b32 v[106:107], v9 offset0:82 offset1:115
	ds_read2_b32 v[108:109], v9 offset0:148 offset1:181
	ds_read2_b32 v[110:111], v9 offset0:214 offset1:247
	ds_read2_b32 v[112:113], v9 offset0:24 offset1:57
	ds_read2_b32 v[114:115], v9 offset0:90 offset1:123
	ds_read2_b32 v[116:117], v9 offset0:156 offset1:189
	ds_read2_b32 v[118:119], v9 offset0:222 offset1:255
	s_waitcnt lgkmcnt(0)
	v_cvt_pk_fp8_f32 v120, v88, v89
	v_cvt_pk_fp8_f32 v121, v92, v93
	v_cvt_pk_fp8_f32 v120, v90, v91 op_sel:[0,0,1]
	v_cvt_pk_fp8_f32 v121, v94, v95 op_sel:[0,0,1]
	v_cvt_pk_fp8_f32 v122, v96, v97
	v_cvt_pk_fp8_f32 v123, v100, v101
	v_cvt_pk_fp8_f32 v122, v98, v99 op_sel:[0,0,1]
	v_cvt_pk_fp8_f32 v123, v102, v103 op_sel:[0,0,1]
	v_cvt_pk_fp8_f32 v124, v104, v105
	v_cvt_pk_fp8_f32 v125, v108, v109
	v_cvt_pk_fp8_f32 v124, v106, v107 op_sel:[0,0,1]
	v_cvt_pk_fp8_f32 v125, v110, v111 op_sel:[0,0,1]
	v_cvt_pk_fp8_f32 v126, v112, v113
	v_cvt_pk_fp8_f32 v127, v116, v117
	v_cvt_pk_fp8_f32 v126, v114, v115 op_sel:[0,0,1]
	v_cvt_pk_fp8_f32 v127, v118, v119 op_sel:[0,0,1]
	s_cmp_eq_u32 s30, 0
	s_cbranch_scc0 .Lcve_pA5d
	global_store_dwordx2 v19, v[120:121], s[28:29]
	global_store_dwordx2 v20, v[122:123], s[28:29]
	global_store_dwordx2 v21, v[124:125], s[28:29]
	global_store_dwordx2 v22, v[126:127], s[28:29]
	s_branch .Lcve_pA5e
; #define LAS __attribute__((address_space(3)))
; __device__ __forceinline__ unsigned cvt_pk_bf16(float lo, float hi) { unsigned r; asm volatile("v_cvt_pk_bf16_f32 %0, %1, %2" : "=v"(r) : "v"(lo), "v"(hi)); return r; }
; __device__ __forceinline__ unsigned cvt4_fp8(float a, float b, float c, float d) { unsigned w = __builtin_amdgcn_cvt_pk_fp8_f32(a, b, 0u, false); return (unsigned)__builtin_amdgcn_cvt_pk_fp8_f32(c, d, (int)w, true); }
; #define LDS_WAIT() asm volatile("s_waitcnt lgkmcnt(0)" ::: "memory")
;     const int kb = item / nblk, nb = item % nblk, k0 = 64 * kb, n0 = 32 * nb;
;     if (f.contig(n0)) {
;         const float* base; int ld; float sc; f(n0, base, ld, sc); sc *= mul;
;         const int r8 = lane >> 3, c4 = (lane & 7) * 4;
;         f32x4 v[8];
; #pragma unroll
;         for (int i = 0; i < 8; ++i) v[i] = __builtin_nontemporal_load((const f32x4*)(base + (size_t)(k0 + 8 * i + r8) * ld + c4));
; #pragma unroll
;         for (int i = 0; i < 8; ++i) { const int kk = 8 * i + r8; const float m = kscale ? sc * kscale[k0 + kk] : sc;
;             scr[kk * 33 + c4 + 0] = v[i][0] * m; scr[kk * 33 + c4 + 1] = v[i][1] * m; scr[kk * 33 + c4 + 2] = v[i][2] * m; scr[kk * 33 + c4 + 3] = v[i][3] * m; }
;     } else {
;         const float* src; int ld; float sc; f(n0 + (lane & 31), src, ld, sc); sc *= mul;
; #pragma unroll 8
;         for (int i = 0; i < 32; ++i) { const int kk = 2 * i + (lane >> 5); float v = src[(size_t)(k0 + kk) * ld] * sc; if (kscale) v *= kscale[k0 + kk]; scr[kk * 33 + (lane & 31)] = v; }
;     }
;     LDS_WAIT(); asm volatile("" ::: "memory");
;     const int c = lane & 7;
; #pragma unroll
;     for (int j = 0; j < 4; ++j) { const int n = (lane >> 3) + 8 * j; const LAS float* s = scr + (8 * c) * 33 + n;
;         if constexpr (F8OUT) {
;             u32x2 o; o.x = cvt4_fp8(s[0 * 33], s[1 * 33], s[2 * 33], s[3 * 33]); o.y = cvt4_fp8(s[4 * 33], s[5 * 33], s[6 * 33], s[7 * 33]);
;             *(u32x2*)((unsigned char*)WT + (size_t)(n0 + n) * K + k0 + 8 * c) = o;
;         } else {
;             u32x4 o; o.x = cvt_pk_bf16(s[0 * 33], s[1 * 33]); o.y = cvt_pk_bf16(s[2 * 33], s[3 * 33]); o.z = cvt_pk_bf16(s[4 * 33], s[5 * 33]); o.w = cvt_pk_bf16(s[6 * 33], s[7 * 33]);
;             *(u32x4*)(WT + (size_t)(n0 + n) * K + k0 + 8 * c) = o; } }
;     LDS_WAIT(); asm volatile("" ::: "memory");
; }
.Lcve_pA5d:
	global_store_dwordx2 v144, v[120:121], s[28:29]
	global_store_dwordx2 v23, v[122:123], s[28:29]
	global_store_dwordx2 v5, v[124:125], s[28:29]
	global_store_dwordx2 v7, v[126:127], s[28:29]
.Lcve_pA5e:
	s_waitcnt vmcnt(4)
	v_pk_mul_f32 v[56:57], v[56:57], s[40:41] op_sel_hi:[1,0]
	v_pk_mul_f32 v[58:59], v[58:59], s[40:41] op_sel_hi:[1,0]
	ds_write2_b32 v128, v56, v57 offset1:1
	ds_write2_b32 v128, v58, v59 offset0:2 offset1:3
	v_pk_mul_f32 v[60:61], v[60:61], s[40:41] op_sel_hi:[1,0]
	v_pk_mul_f32 v[62:63], v[62:63], s[40:41] op_sel_hi:[1,0]
	ds_write2_b32 v129, v60, v61 offset1:1
	ds_write2_b32 v129, v62, v63 offset0:2 offset1:3
	v_pk_mul_f32 v[64:65], v[64:65], s[40:41] op_sel_hi:[1,0]
	v_pk_mul_f32 v[66:67], v[66:67], s[40:41] op_sel_hi:[1,0]
	ds_write2_b32 v130, v64, v65 offset1:1
	ds_write2_b32 v130, v66, v67 offset0:2 offset1:3
	v_pk_mul_f32 v[68:69], v[68:69], s[40:41] op_sel_hi:[1,0]
	v_pk_mul_f32 v[70:71], v[70:71], s[40:41] op_sel_hi:[1,0]
	ds_write2_b32 v131, v68, v69 offset1:1
	ds_write2_b32 v131, v70, v71 offset0:2 offset1:3
	v_pk_mul_f32 v[72:73], v[72:73], s[40:41] op_sel_hi:[1,0]
	v_pk_mul_f32 v[74:75], v[74:75], s[40:41] op_sel_hi:[1,0]
	ds_write2_b32 v132, v72, v73 offset1:1
	ds_write2_b32 v132, v74, v75 offset0:2 offset1:3
	v_pk_mul_f32 v[76:77], v[76:77], s[40:41] op_sel_hi:[1,0]
	v_pk_mul_f32 v[78:79], v[78:79], s[40:41] op_sel_hi:[1,0]
	ds_write2_b32 v133, v76, v77 offset1:1
	ds_write2_b32 v133, v78, v79 offset0:2 offset1:3
	v_pk_mul_f32 v[80:81], v[80:81], s[40:41] op_sel_hi:[1,0]
	v_pk_mul_f32 v[82:83], v[82:83], s[40:41] op_sel_hi:[1,0]
	ds_write2_b32 v134, v80, v81 offset1:1
	ds_write2_b32 v134, v82, v83 offset0:2 offset1:3
	v_pk_mul_f32 v[84:85], v[84:85], s[40:41] op_sel_hi:[1,0]
	v_pk_mul_f32 v[86:87], v[86:87], s[40:41] op_sel_hi:[1,0]
	ds_write2_b32 v135, v84, v85 offset1:1
	ds_write2_b32 v135, v86, v87 offset0:2 offset1:3
	s_waitcnt lgkmcnt(0)
	ds_read2_b32 v[88:89], v9 offset0:0 offset1:33
	ds_read2_b32 v[90:91], v9 offset0:66 offset1:99
	ds_read2_b32 v[92:93], v9 offset0:132 offset1:165
	ds_read2_b32 v[94:95], v9 offset0:198 offset1:231
	ds_read2_b32 v[96:97], v9 offset0:8 offset1:41
	ds_read2_b32 v[98:99], v9 offset0:74 offset1:107
	ds_read2_b32 v[100:101], v9 offset0:140 offset1:173
	ds_read2_b32 v[102:103], v9 offset0:206 offset1:239
	ds_read2_b32 v[104:105], v9 offset0:16 offset1:49
	ds_read2_b32 v[106:107], v9 offset0:82 offset1:115
	ds_read2_b32 v[108:109], v9 offset0:148 offset1:181
	ds_read2_b32 v[110:111], v9 offset0:214 offset1:247
	ds_read2_b32 v[112:113], v9 offset0:24 offset1:57
	ds_read2_b32 v[114:115], v9 offset0:90 offset1:123
	ds_read2_b32 v[116:117], v9 offset0:156 offset1:189
	ds_read2_b32 v[118:119], v9 offset0:222 offset1:255
	s_waitcnt lgkmcnt(0)
	v_cvt_pk_fp8_f32 v120, v88, v89
	v_cvt_pk_fp8_f32 v121, v92, v93
	v_cvt_pk_fp8_f32 v120, v90, v91 op_sel:[0,0,1]
	v_cvt_pk_fp8_f32 v121, v94, v95 op_sel:[0,0,1]
	v_cvt_pk_fp8_f32 v122, v96, v97
	v_cvt_pk_fp8_f32 v123, v100, v101
	v_cvt_pk_fp8_f32 v122, v98, v99 op_sel:[0,0,1]
	v_cvt_pk_fp8_f32 v123, v102, v103 op_sel:[0,0,1]
	v_cvt_pk_fp8_f32 v124, v104, v105
	v_cvt_pk_fp8_f32 v125, v108, v109
	v_cvt_pk_fp8_f32 v124, v106, v107 op_sel:[0,0,1]
	v_cvt_pk_fp8_f32 v125, v110, v111 op_sel:[0,0,1]
	v_cvt_pk_fp8_f32 v126, v112, v113
	v_cvt_pk_fp8_f32 v127, v116, v117
	v_cvt_pk_fp8_f32 v126, v114, v115 op_sel:[0,0,1]
	v_cvt_pk_fp8_f32 v127, v118, v119 op_sel:[0,0,1]
	s_cmp_eq_u32 s38, 0
	s_cbranch_scc0 .Lcve_pB6d
	global_store_dwordx2 v19, v[120:121], s[36:37]
	global_store_dwordx2 v20, v[122:123], s[36:37]
	global_store_dwordx2 v21, v[124:125], s[36:37]
	global_store_dwordx2 v22, v[126:127], s[36:37]
	s_branch .Lcve_pB6e
.Lcve_pB6d:
	global_store_dwordx2 v144, v[120:121], s[36:37]
	global_store_dwordx2 v23, v[122:123], s[36:37]
	global_store_dwordx2 v5, v[124:125], s[36:37]
	global_store_dwordx2 v7, v[126:127], s[36:37]
.Lcve_pB6e:
	s_sub_u32 s21, s21, 2
	s_branch .Lcve_loop
.Lcve_tail:
	s_cmp_eq_u32 s21, 0
	s_cbranch_scc1 .Lcve_fin
	s_lshr_b32 s23, s22, 8
	s_mul_i32 s23, s23, 3121
	s_lshr_b32 s23, s23, 16
	s_mul_i32 s24, s23, 5376
	s_sub_u32 s24, s22, s24
	s_cmp_lt_u32 s24, 3584
	s_cbranch_scc0 .Lcve_DA7
	s_lshr_b32 s25, s24, 5
	s_mul_i32 s25, s25, 9363
	s_lshr_b32 s25, s25, 16
	s_mul_i32 s41, s25, 224
	s_sub_u32 s41, s24, s41
	s_and_b32 s42, s41, 7
	s_cmp_lt_u32 s42, 4
	s_cselect_b32 s26, s12, s14
	s_cselect_b32 s27, s13, s15
	s_mul_i32 s43, s23, 14680064
	s_mul_i32 s44, s25, 917504
	s_add_u32 s43, s43, s44
	s_lshr_b32 s44, s41, 3
	s_lshl_b32 s44, s44, 9
	s_add_u32 s43, s43, s44
	s_and_b32 s44, s42, 3
	s_lshl_b32 s44, s44, 7
	s_add_u32 s43, s43, s44
	s_add_u32 s26, s26, s43
	s_addc_u32 s27, s27, 0
	s_mul_i32 s43, s23, 7340032
	s_lshl_b32 s44, s41, 15
	s_add_u32 s43, s43, s44
	s_lshl_b32 s44, s25, 6
	s_add_u32 s43, s43, s44
	s_add_u32 s43, s43, 0x4400000
	s_add_u32 s28, s18, s43
	s_addc_u32 s29, s19, 0
	s_mov_b32 s30, 0
	s_mov_b32 s32, 0x42800000
	s_branch .Lcve_EA7

;     __device__ __forceinline__ bool contig(int n0) const { return (n0 % 192) < 128; }
;     const int kb = item / nblk, nb = item % nblk, k0 = 64 * kb, n0 = 32 * nb;
;     if (f.contig(n0)) {
;         const float* base; int ld; float sc; f(n0, base, ld, sc); sc *= mul;
;         const int r8 = lane >> 3, c4 = (lane & 7) * 4;
;         f32x4 v[8];
; #pragma unroll
;         for (int i = 0; i < 8; ++i) v[i] = __builtin_nontemporal_load((const f32x4*)(base + (size_t)(k0 + 8 * i + r8) * ld + c4));
; #pragma unroll
;         for (int i = 0; i < 8; ++i) { const int kk = 8 * i + r8; const float m = kscale ? sc * kscale[k0 + kk] : sc;
;             scr[kk * 33 + c4 + 0] = v[i][0] * m; scr[kk * 33 + c4 + 1] = v[i][1] * m; scr[kk * 33 + c4 + 2] = v[i][2] * m; scr[kk * 33 + c4 + 3] = v[i][3] * m; }
.Lcve_EA7:
	s_cmp_eq_u32 s30, 0
	s_cbranch_scc0 .Lcve_iA8d
	global_load_dwordx4 v[24:27], v11, s[26:27] nt
	global_load_dwordx4 v[28:31], v12, s[26:27] nt
	global_load_dwordx4 v[32:35], v13, s[26:27] nt
	global_load_dwordx4 v[36:39], v14, s[26:27] nt
	global_load_dwordx4 v[40:43], v15, s[26:27] nt
	global_load_dwordx4 v[44:47], v16, s[26:27] nt
	global_load_dwordx4 v[48:51], v17, s[26:27] nt
	global_load_dwordx4 v[52:55], v18, s[26:27] nt
	s_branch .Lcve_iA8e

; #define LAS __attribute__((address_space(3)))
; __device__ __forceinline__ unsigned cvt_pk_bf16(float lo, float hi) { unsigned r; asm volatile("v_cvt_pk_bf16_f32 %0, %1, %2" : "=v"(r) : "v"(lo), "v"(hi)); return r; }
; __device__ __forceinline__ unsigned cvt4_fp8(float a, float b, float c, float d) { unsigned w = __builtin_amdgcn_cvt_pk_fp8_f32(a, b, 0u, false); return (unsigned)__builtin_amdgcn_cvt_pk_fp8_f32(c, d, (int)w, true); }
; #define LDS_WAIT() asm volatile("s_waitcnt lgkmcnt(0)" ::: "memory")
;     ...
;         for (int i = 0; i < 8; ++i) { const int kk = 8 * i + r8; const float m = kscale ? sc * kscale[k0 + kk] : sc;
;             scr[kk * 33 + c4 + 0] = v[i][0] * m; scr[kk * 33 + c4 + 1] = v[i][1] * m; scr[kk * 33 + c4 + 2] = v[i][2] * m; scr[kk * 33 + c4 + 3] = v[i][3] * m; }
;     } else {
;         const float* src; int ld; float sc; f(n0 + (lane & 31), src, ld, sc); sc *= mul;
; #pragma unroll 8
;         for (int i = 0; i < 32; ++i) { const int kk = 2 * i + (lane >> 5); float v = src[(size_t)(k0 + kk) * ld] * sc; if (kscale) v *= kscale[k0 + kk]; scr[kk * 33 + (lane & 31)] = v; }
;     }
;     LDS_WAIT(); asm volatile("" ::: "memory");
;     const int c = lane & 7;
; #pragma unroll
;     for (int j = 0; j < 4; ++j) { const int n = (lane >> 3) + 8 * j; const LAS float* s = scr + (8 * c) * 33 + n;
;         if constexpr (F8OUT) {
;             u32x2 o; o.x = cvt4_fp8(s[0 * 33], s[1 * 33], s[2 * 33], s[3 * 33]); o.y = cvt4_fp8(s[4 * 33], s[5 * 33], s[6 * 33], s[7 * 33]);
;             *(u32x2*)((unsigned char*)WT + (size_t)(n0 + n) * K + k0 + 8 * c) = o;
;         } else {
;             u32x4 o; o.x = cvt_pk_bf16(s[0 * 33], s[1 * 33]); o.y = cvt_pk_bf16(s[2 * 33], s[3 * 33]); o.z = cvt_pk_bf16(s[4 * 33], s[5 * 33]); o.w = cvt_pk_bf16(s[6 * 33], s[7 * 33]);
;             *(u32x4*)(WT + (size_t)(n0 + n) * K + k0 + 8 * c) = o; } }
;     LDS_WAIT(); asm volatile("" ::: "memory");
; }
.Lcve_iA8e:
	s_waitcnt vmcnt(0)
	v_pk_mul_f32 v[24:25], v[24:25], s[32:33] op_sel_hi:[1,0]
	v_pk_mul_f32 v[26:27], v[26:27], s[32:33] op_sel_hi:[1,0]
	ds_write2_b32 v128, v24, v25 offset1:1
	ds_write2_b32 v128, v26, v27 offset0:2 offset1:3
	v_pk_mul_f32 v[28:29], v[28:29], s[32:33] op_sel_hi:[1,0]
	v_pk_mul_f32 v[30:31], v[30:31], s[32:33] op_sel_hi:[1,0]
	ds_write2_b32 v129, v28, v29 offset1:1
	ds_write2_b32 v129, v30, v31 offset0:2 offset1:3
	v_pk_mul_f32 v[32:33], v[32:33], s[32:33] op_sel_hi:[1,0]
	v_pk_mul_f32 v[34:35], v[34:35], s[32:33] op_sel_hi:[1,0]
	ds_write2_b32 v130, v32, v33 offset1:1
	ds_write2_b32 v130, v34, v35 offset0:2 offset1:3
	v_pk_mul_f32 v[36:37], v[36:37], s[32:33] op_sel_hi:[1,0]
	v_pk_mul_f32 v[38:39], v[38:39], s[32:33] op_sel_hi:[1,0]
	ds_write2_b32 v131, v36, v37 offset1:1
	ds_write2_b32 v131, v38, v39 offset0:2 offset1:3
	v_pk_mul_f32 v[40:41], v[40:41], s[32:33] op_sel_hi:[1,0]
	v_pk_mul_f32 v[42:43], v[42:43], s[32:33] op_sel_hi:[1,0]
	ds_write2_b32 v132, v40, v41 offset1:1
	ds_write2_b32 v132, v42, v43 offset0:2 offset1:3
	v_pk_mul_f32 v[44:45], v[44:45], s[32:33] op_sel_hi:[1,0]
	v_pk_mul_f32 v[46:47], v[46:47], s[32:33] op_sel_hi:[1,0]
	ds_write2_b32 v133, v44, v45 offset1:1
	ds_write2_b32 v133, v46, v47 offset0:2 offset1:3
	v_pk_mul_f32 v[48:49], v[48:49], s[32:33] op_sel_hi:[1,0]
	v_pk_mul_f32 v[50:51], v[50:51], s[32:33] op_sel_hi:[1,0]
	ds_write2_b32 v134, v48, v49 offset1:1
	ds_write2_b32 v134, v50, v51 offset0:2 offset1:3
	v_pk_mul_f32 v[52:53], v[52:53], s[32:33] op_sel_hi:[1,0]
	v_pk_mul_f32 v[54:55], v[54:55], s[32:33] op_sel_hi:[1,0]
	ds_write2_b32 v135, v52, v53 offset1:1
	ds_write2_b32 v135, v54, v55 offset0:2 offset1:3
	s_waitcnt lgkmcnt(0)
	ds_read2_b32 v[88:89], v9 offset0:0 offset1:33
	ds_read2_b32 v[90:91], v9 offset0:66 offset1:99
	ds_read2_b32 v[92:93], v9 offset0:132 offset1:165
	ds_read2_b32 v[94:95], v9 offset0:198 offset1:231
	ds_read2_b32 v[96:97], v9 offset0:8 offset1:41
	ds_read2_b32 v[98:99], v9 offset0:74 offset1:107
	ds_read2_b32 v[100:101], v9 offset0:140 offset1:173
	ds_read2_b32 v[102:103], v9 offset0:206 offset1:239
	ds_read2_b32 v[104:105], v9 offset0:16 offset1:49
	ds_read2_b32 v[106:107], v9 offset0:82 offset1:115
	ds_read2_b32 v[108:109], v9 offset0:148 offset1:181
	ds_read2_b32 v[110:111], v9 offset0:214 offset1:247
	ds_read2_b32 v[112:113], v9 offset0:24 offset1:57
	ds_read2_b32 v[114:115], v9 offset0:90 offset1:123
	ds_read2_b32 v[116:117], v9 offset0:156 offset1:189
	ds_read2_b32 v[118:119], v9 offset0:222 offset1:255
	s_waitcnt lgkmcnt(0)
	v_cvt_pk_fp8_f32 v120, v88, v89
	v_cvt_pk_fp8_f32 v121, v92, v93
	v_cvt_pk_fp8_f32 v120, v90, v91 op_sel:[0,0,1]
	v_cvt_pk_fp8_f32 v121, v94, v95 op_sel:[0,0,1]
	v_cvt_pk_fp8_f32 v122, v96, v97
	v_cvt_pk_fp8_f32 v123, v100, v101
	v_cvt_pk_fp8_f32 v122, v98, v99 op_sel:[0,0,1]
	v_cvt_pk_fp8_f32 v123, v102, v103 op_sel:[0,0,1]
	v_cvt_pk_fp8_f32 v124, v104, v105
	v_cvt_pk_fp8_f32 v125, v108, v109
	v_cvt_pk_fp8_f32 v124, v106, v107 op_sel:[0,0,1]
	v_cvt_pk_fp8_f32 v125, v110, v111 op_sel:[0,0,1]
	v_cvt_pk_fp8_f32 v126, v112, v113
	v_cvt_pk_fp8_f32 v127, v116, v117
	v_cvt_pk_fp8_f32 v126, v114, v115 op_sel:[0,0,1]
	v_cvt_pk_fp8_f32 v127, v118, v119 op_sel:[0,0,1]
	s_cmp_eq_u32 s30, 0
	s_cbranch_scc0 .Lcve_pA9d
	global_store_dwordx2 v19, v[120:121], s[28:29]
	global_store_dwordx2 v20, v[122:123], s[28:29]
	global_store_dwordx2 v21, v[124:125], s[28:29]
	global_store_dwordx2 v22, v[126:127], s[28:29]
	s_branch .Lcve_pA9e

; #define LAS __attribute__((address_space(3)))
; __device__ __forceinline__ int oi(int k) { asm volatile("" : "+s"(k)); return k; }
; #define opq(p) ((p) + oz())
; __device__ __forceinline__ const float* gfp(const float* p) { ASSUME_GLOBAL(p); return p; }
; #define ws opq(a.ws)
; __device__ __forceinline__ void cvt_moe(const Args& a, int ml, LAS float* scr, int gw, int NGW, int lane) {
;     asm volatile("" : "+v"(lane));
;     constexpr int I_GU = (DM / 64) * (2 * FFE / 32), I_D = (FFE / 64) * (DM / 32), I_E = I_GU + I_D;
;     const float* wg = gfp(a.in[oi(19)]) + (size_t)ml * NEXP * DM * FFE; const float* wu = gfp(a.in[oi(20)]) + (size_t)ml * NEXP * DM * FFE; const float* wd = gfp(a.in[oi(21)]) + (size_t)ml * NEXP * FFE * DM;
;     unsigned char* wsl = opq(a.ws); bf16_t* mgu = (bf16_t*)(wsl + WS_MGU); bf16_t* md = (bf16_t*)(wsl + WS_MD);
;     for (int it = gw; it < NEXP * I_E; it += NGW) {
;         const int e = it / I_E; int r = it % I_E;
;         if (r < I_GU) { MapGU f{wg + (size_t)e * DM * FFE, wu + (size_t)e * DM * FFE, FFE}; cvt_item<MapGU, true>(f, nullptr, DM, (bf16_t*)((unsigned char*)mgu + (size_t)e * 2 * FFE * DM), scr, r, 2 * FFE / 32, lane, W8_GU); }
;         else { r -= I_GU; MapPlain f{wd + (size_t)e * FFE * DM, DM}; cvt_item<MapPlain, true>(f, nullptr, FFE, (bf16_t*)((unsigned char*)md + (size_t)e * DM * FFE), scr, r, DM / 32, lane, W8_D); }
;     }
; }
.Lcve_pA9e:
.Lcve_fin:
	s_mov_b64 exec, s[8:9]
	v_readlane_b32 s8, v145, 0
	v_readlane_b32 s9, v145, 1
	v_readlane_b32 s10, v145, 2
	v_readlane_b32 s11, v145, 3
	v_readlane_b32 s12, v145, 4
	v_readlane_b32 s13, v145, 5
	v_readlane_b32 s14, v145, 6
	v_readlane_b32 s15, v145, 7
	v_readlane_b32 s16, v145, 8
	v_readlane_b32 s17, v145, 9
	v_readlane_b32 s18, v145, 10
	v_readlane_b32 s19, v145, 11
	v_readlane_b32 s20, v145, 12
	v_readlane_b32 s21, v145, 13
	v_readlane_b32 s22, v145, 14
	v_readlane_b32 s23, v145, 15
	v_readlane_b32 s24, v145, 16
	v_readlane_b32 s25, v145, 17
	v_readlane_b32 s26, v145, 18
	v_readlane_b32 s27, v145, 19
	v_readlane_b32 s28, v145, 20
	v_readlane_b32 s29, v145, 21
	v_readlane_b32 s30, v145, 22
	v_readlane_b32 s31, v145, 23
	v_readlane_b32 s32, v145, 24
	v_readlane_b32 s33, v145, 25
	v_readlane_b32 s34, v145, 26
	v_readlane_b32 s35, v145, 27
	v_readlane_b32 s36, v145, 28
	v_readlane_b32 s37, v145, 29
	v_readlane_b32 s38, v145, 30
	v_readlane_b32 s39, v145, 31
	v_readlane_b32 s40, v145, 32
	v_readlane_b32 s41, v145, 33
	v_readlane_b32 s42, v145, 34
	v_readlane_b32 s43, v145, 35
	v_readlane_b32 s44, v145, 36
	v_readlane_b32 s45, v145, 37
	v_readlane_b32 s46, v145, 38
	v_readlane_b32 s47, v145, 39
	s_nop 4
.Lcve_done:
	s_branch .LBB0_517
.LBB0_515:
	s_mov_b64 s[0:1], 0

; __device__ __forceinline__ int fresh_lane() { int t = threadIdx.x; asm volatile("" : "+v"(t)); return t & 63; }
; __device__ __forceinline__ int oi(int k) { asm volatile("" : "+s"(k)); return k; }
; __device__ __forceinline__ const float* gfp(const float* p) { ASSUME_GLOBAL(p); return p; }
; #define ws opq(a.ws)
; #define PH_BEGIN(k) if (lo <= ph && ph < hi) { if constexpr ((EN >> (k)) & 1) for (int rep_ = 0; rep_ < ((((REP) >> (k)) & 1) ? 2 : 1); ++rep_) {
; #define PH_END() } if (ph + 1 < hi) { if (ph == 0) grid.sync(); else xcd_barrier(xbar); } } ++ph;
; __global__ void __launch_bounds__(512, 2) mega_fwd(Args a) {
;     ...
;         PH_BEGIN(5)
;         { if (moe) ln_pass<0, true, true, true>(a, Y, nullptr, gfp(a.in[oi(11)]) + l * DM, gfp(a.in[oi(12)]) + l * DM, Xf, (bf16_t*)(ws + WS_XB8), gfp(a.in[oi(18)]) + (size_t)li * DM * 8, ctl + CW_CNT + 8 * li, gw, NGW, fresh_lane(), lds);
;           else ln_pass<0, false, true, true>(a, Y, nullptr, gfp(a.in[oi(11)]) + l * DM, gfp(a.in[oi(12)]) + l * DM, Xf, (bf16_t*)(ws + WS_XB8), nullptr, nullptr, gw, NGW, fresh_lane(), lds);
;           if (l == 2) cvt_moe(a, 1, scr, gw, NGW, fresh_lane()); }
;         PH_END()
.LBB0_1078:
	s_cmp_lg_u32 s90, 2
	s_branch .LBB0_1090
	v_mov_b32_e32 v0, v166
	v_readlane_b32 s10, v252, 26
	v_readlane_b32 s11, v252, 27
	v_and_b32_e32 v0, 63, v0
	s_mov_b32 s8, 19
	s_mov_b32 s6, 20
	s_mov_b32 s2, 21
	s_mov_b64 s[4:5], 0
	s_andn2_b64 vcc, exec, s[10:11]
	s_cbranch_vccnz .LBB0_1090
	s_ashr_i32 s9, s8, 31
	s_lshl_b64 s[8:9], s[8:9], 3
	s_add_u32 s8, s72, s8
	s_addc_u32 s9, s73, s9
	s_load_dwordx2 s[8:9], s[8:9], 0x0
	v_ashrrev_i32_e32 v3, 3, v0
	v_lshlrev_b32_e32 v2, 2, v0
	v_lshlrev_b32_e32 v0, 3, v0
	v_and_b32_e32 v2, 28, v2
	s_waitcnt lgkmcnt(0)
	s_add_u32 s16, s8, 0x7000000
	s_addc_u32 s17, s9, 0
	s_ashr_i32 s7, s6, 31
	s_lshl_b64 s[6:7], s[6:7], 3
	s_add_u32 s6, s72, s6
	s_addc_u32 s7, s73, s7
	s_ashr_i32 s3, s2, 31
	s_lshl_b64 s[2:3], s[2:3], 3
	s_add_u32 s8, s72, s2
	s_addc_u32 s9, s73, s3
	s_load_dwordx2 s[2:3], s[6:7], 0x0
	s_nop 0
	s_load_dwordx2 s[6:7], s[8:9], 0x0
	s_movk_i32 s8, 0x84
	v_mul_lo_u32 v6, v3, s8
	v_readlane_b32 s8, v251, 5
	v_and_b32_e32 v4, 56, v0
	s_waitcnt lgkmcnt(0)
	s_add_u32 s18, s6, 0x7000000
	s_addc_u32 s19, s7, 0
	s_add_u32 s4, s14, s4
	s_addc_u32 s5, s15, s5
	s_add_u32 s24, s4, 0x4400000
	s_addc_u32 s25, s5, 0
	s_add_u32 s26, s4, 0xb400000
	s_addc_u32 s28, s5, 0
	v_readlane_b32 s4, v254, 2
	s_mov_b32 s6, s4
	s_lshl_b32 s4, s4, 5
	v_lshl_add_u32 v7, v2, 2, s8
	v_mul_u32_u24_e32 v0, 0x84, v4
	v_lshlrev_b32_e32 v8, 2, v3
	s_add_i32 s29, s4, 0xfffe4000
	s_lshl_b32 s4, s6, 1
	v_add_u32_e32 v16, 8, v3
	v_add_u32_e32 v17, 16, v3
	v_add_u32_e32 v18, 24, v3
	v_mov_b32_e32 v5, v1
	v_add3_u32 v19, s8, v0, v8
	s_add_i32 s30, s4, 0xffffe400
	v_add_u32_e32 v20, v7, v6
	s_mov_b32 s31, s6
	v_readlane_b32 s5, v254, 3
	s_branch .LBB0_1083
